# router top-4: wave max via DPP row ops + row_bcast + readlane instead of six ds_bpermute round trips (exact, max is order independent)
# speedup vs baseline: 1.0080x; 1.0041x over previous
; DI float wave_max(float v) { for (int o = 32; o >= 1; o >>= 1) v = fmaxf(v, shx(v, o)); return v; }
; DI int crow(int i, int hh) { return (i & 3) + 8 * (i >> 2) + 4 * hh; }
; DI void router_phase(const P& p, int l, int ntok, unsigned char* lds) {
;     ...
;     __syncthreads();
;     f32x16 acc;
; #pragma unroll
;     for (int i = 0; i < 16; ++i) acc[i] = 0.f;
;     {
;       const float* ar = tile + r * 1025 + w * 128 + hh;
;       const float* brp = wr + (size_t)(w * 128 + hh) * 32 + r;
; #pragma unroll 8
;       for (int s2 = 0; s2 < 64; ++s2) acc = __builtin_amdgcn_mfma_f32_32x32x2f32(ar[2 * s2], brp[(size_t)2 * s2 * 32], acc, 0, 0, 0);
;     }
;     __syncthreads();
;     float* part = tile;
; #pragma unroll
;     for (int i = 0; i < 16; ++i) part[(w * 32 + crow(i, hh)) * 33 + r] = acc[i];
;     __syncthreads();
; #pragma unroll
;     for (int q = 0; q < 4; ++q) {
;       int tl = w * 4 + q;
;       int tok = tbase + c0 + tl;
;       bool valid = (c0 + tl) < per;
;       float v = br[r];
; #pragma unroll
;       for (int k = 0; k < 8; ++k) v += part[(k * 32 + tl) * 33 + r];
;       int se[4]; float sv[4];
; #pragma unroll
;       for (int k = 0; k < 4; ++k) {
;         float m = wave_max(v);
;         unsigned long long mask = __ballot(v == m);
;         int idx = __ffsll((long long)mask) - 1;
;         se[k] = idx & 31; sv[k] = m;
;         if (r == (idx & 31)) v = -3.0e38f;
;       }
;       float e1 = __expf(sv[1] - sv[0]), e2 = __expf(sv[2] - sv[0]), e3 = __expf(sv[3] - sv[0]);
.LBB0_1259:
	v_lshl_add_u64 v[20:21], v[50:51], 0, s[0:1]
	global_load_dword v19, v[20:21], off
	global_load_dword v24, v[20:21], off offset:256
	global_load_dword v25, v[20:21], off offset:512
	global_load_dword v26, v[20:21], off offset:768
	global_load_dword v27, v[20:21], off offset:1024
	ds_read2_b32 v[22:23], v18 offset1:2
	global_load_dword v28, v[20:21], off offset:1280
	global_load_dword v29, v[20:21], off offset:1536
	global_load_dword v53, v[20:21], off offset:1792
	ds_read2_b32 v[20:21], v18 offset0:4 offset1:6
	s_add_u32 s0, s0, 0x800
	s_addc_u32 s1, s1, 0
	s_cmpk_eq_i32 s0, 0x4000
	s_waitcnt vmcnt(7) lgkmcnt(1)
	v_mfma_f32_32x32x2_f32 v[2:17], v22, v19, v[2:17]
	s_waitcnt vmcnt(6)
	v_mfma_f32_32x32x2_f32 v[2:17], v23, v24, v[2:17]
	s_waitcnt vmcnt(5) lgkmcnt(0)
	v_mfma_f32_32x32x2_f32 v[2:17], v20, v25, v[2:17]
	s_waitcnt vmcnt(4)
	v_mfma_f32_32x32x2_f32 v[2:17], v21, v26, v[2:17]
	ds_read2_b32 v[20:21], v18 offset0:8 offset1:10
	s_waitcnt vmcnt(3) lgkmcnt(0)
	v_mfma_f32_32x32x2_f32 v[2:17], v20, v27, v[2:17]
	s_waitcnt vmcnt(2)
	v_mfma_f32_32x32x2_f32 v[2:17], v21, v28, v[2:17]
	ds_read2_b32 v[20:21], v18 offset0:12 offset1:14
	v_add_u32_e32 v18, 64, v18
	s_waitcnt vmcnt(1) lgkmcnt(0)
	v_mfma_f32_32x32x2_f32 v[2:17], v20, v29, v[2:17]
	s_waitcnt vmcnt(0)
	v_mfma_f32_32x32x2_f32 v[2:17], v21, v53, v[2:17]
	s_cbranch_scc0 .LBB0_1259
	s_barrier
	s_nop 15
	ds_write2_b32 v72, v2, v3 offset1:33
	ds_write2_b32 v72, v4, v5 offset0:66 offset1:99
	v_add_u32_e32 v2, 0x400, v72
	ds_write2_b32 v2, v6, v7 offset0:8 offset1:41
	ds_write2_b32 v2, v8, v9 offset0:74 offset1:107
	v_add_u32_e32 v2, 0x800, v72
	ds_write2_b32 v2, v10, v11 offset0:16 offset1:49
	ds_write2_b32 v2, v12, v13 offset0:82 offset1:115
	v_add_u32_e32 v2, 0xc00, v72
	ds_write2_b32 v2, v14, v15 offset0:24 offset1:57
	ds_write2_b32 v2, v16, v17 offset0:90 offset1:123
	s_waitcnt lgkmcnt(0)
	s_barrier
	global_load_dword v2, v[30:31], off
	ds_read_b32 v4, v73
	ds_read_b32 v5, v73 offset:4224
	ds_read_b32 v6, v73 offset:8448
	ds_read_b32 v7, v73 offset:12672
	ds_read_b32 v8, v73 offset:16896
	ds_read_b32 v9, v73 offset:21120
	ds_read_b32 v10, v73 offset:25344
	ds_read_b32 v11, v73 offset:29568
	v_mov_b32_e32 v3, v215
	s_add_i32 s22, s20, s19
	v_lshlrev_b32_e32 v3, 2, v3
	v_bitop3_b32 v3, v3, s76, v220 bitop3:0x6c
	s_waitcnt vmcnt(0) lgkmcnt(7)
	v_add_f32_e32 v2, v2, v4
	s_waitcnt lgkmcnt(6)
	v_add_f32_e32 v2, v2, v5
	s_waitcnt lgkmcnt(5)
	v_add_f32_e32 v2, v2, v6
	s_waitcnt lgkmcnt(4)
	v_add_f32_e32 v2, v2, v7
	s_waitcnt lgkmcnt(3)
	v_add_f32_e32 v2, v2, v8
	s_waitcnt lgkmcnt(2)
	v_add_f32_e32 v2, v2, v9
	s_waitcnt lgkmcnt(1)
	v_add_f32_e32 v2, v2, v10
	s_waitcnt lgkmcnt(0)
	v_add_f32_e32 v4, v2, v11
	s_nop 1
	v_max_f32_dpp v150, v4, v4 quad_perm:[1,0,3,2] row_mask:0xf bank_mask:0xf
	s_nop 1
	v_max_f32_dpp v150, v150, v150 quad_perm:[2,3,0,1] row_mask:0xf bank_mask:0xf
	s_nop 1
	v_max_f32_dpp v150, v150, v150 row_half_mirror row_mask:0xf bank_mask:0xf
	s_nop 1
	v_max_f32_dpp v150, v150, v150 row_mirror row_mask:0xf bank_mask:0xf
	s_nop 1
	v_max_f32_dpp v150, v150, v150 row_bcast:15 row_mask:0xa bank_mask:0xf
	s_nop 1
	v_max_f32_dpp v150, v150, v150 row_bcast:31 row_mask:0xc bank_mask:0xf
	s_nop 1
	v_readlane_b32 s32, v150, 63
	s_nop 1
	v_mov_b32_e32 v2, s32
	v_mov_b32_e32 v3, v215
	v_mov_b32_e32 v5, v215
	v_lshlrev_b32_e32 v3, 2, v3
	s_waitcnt lgkmcnt(0)
	v_max_f32_e32 v2, v2, v2
	v_bitop3_b32 v3, v3, 64, v220 bitop3:0x6c
	v_max_f32_e32 v2, v4, v2
	v_mov_b32_e32 v3, v2
	v_mov_b32_e32 v6, v215
	v_lshlrev_b32_e32 v5, 2, v5
	v_bitop3_b32 v5, v5, 32, v220 bitop3:0x6c
	s_waitcnt lgkmcnt(0)
	v_max_f32_e32 v3, v3, v3
	v_max_f32_e32 v2, v2, v3
	v_mov_b32_e32 v3, v2
	v_mov_b32_e32 v5, v215
	v_mov_b32_e32 v7, v215
	v_lshlrev_b32_e32 v5, 2, v5
	s_waitcnt lgkmcnt(0)
	v_max_f32_e32 v3, v3, v3
	v_bitop3_b32 v5, v5, 16, v220 bitop3:0x6c
	v_max_f32_e32 v2, v2, v3
	v_mov_b32_e32 v3, v2
	v_mov_b32_e32 v5, v215
	v_mov_b32_e32 v8, v215
	v_lshlrev_b32_e32 v5, 2, v5
	s_waitcnt lgkmcnt(0)
	v_max_f32_e32 v3, v3, v3
	v_bitop3_b32 v5, v5, 8, v220 bitop3:0x6c
	v_max_f32_e32 v2, v2, v3
	v_mov_b32_e32 v3, v2
	v_mov_b32_e32 v5, v215
	s_waitcnt lgkmcnt(0)
	v_max_f32_e32 v3, v3, v3
	v_lshlrev_b32_e32 v5, 2, v5
	v_bitop3_b32 v5, v5, 4, v220 bitop3:0x6c
	v_max_f32_e32 v2, v2, v3
	v_mov_b32_e32 v3, v2
	v_mov_b32_e32 v5, v215
	s_waitcnt lgkmcnt(0)
	v_max_f32_e32 v3, v3, v3
	v_max_f32_e32 v2, v2, v3
	v_cmp_eq_f32_e32 vcc, v4, v2
	s_ff1_i32_b64 s0, vcc
	s_and_b32 s0, s0, 31
	s_cmp_lg_u64 vcc, 0
	s_cselect_b32 s23, s0, 31
	v_lshlrev_b32_e32 v5, 2, v5
	v_cmp_ne_u32_e32 vcc, s23, v37
	v_bitop3_b32 v5, v5, s76, v220 bitop3:0x6c
	s_nop 0
	v_cndmask_b32_e32 v4, v223, v4, vcc
	s_nop 1
	v_max_f32_dpp v150, v4, v4 quad_perm:[1,0,3,2] row_mask:0xf bank_mask:0xf
	s_nop 1
	v_max_f32_dpp v150, v150, v150 quad_perm:[2,3,0,1] row_mask:0xf bank_mask:0xf
	s_nop 1
	v_max_f32_dpp v150, v150, v150 row_half_mirror row_mask:0xf bank_mask:0xf
	s_nop 1
	v_max_f32_dpp v150, v150, v150 row_mirror row_mask:0xf bank_mask:0xf
	s_nop 1
	v_max_f32_dpp v150, v150, v150 row_bcast:15 row_mask:0xa bank_mask:0xf
	s_nop 1
	v_max_f32_dpp v150, v150, v150 row_bcast:31 row_mask:0xc bank_mask:0xf
	s_nop 1
	v_readlane_b32 s32, v150, 63
	s_nop 1
	v_mov_b32_e32 v3, s32
	v_mov_b32_e32 v5, v215
	s_waitcnt lgkmcnt(0)
	v_max_f32_e32 v3, v3, v3
	v_lshlrev_b32_e32 v5, 2, v5
	v_bitop3_b32 v5, v5, 64, v220 bitop3:0x6c
	v_max_f32_e32 v3, v4, v3
	v_mov_b32_e32 v5, v3
	v_lshlrev_b32_e32 v6, 2, v6
	v_bitop3_b32 v6, v6, 32, v220 bitop3:0x6c
	s_waitcnt lgkmcnt(0)
	v_max_f32_e32 v5, v5, v5
	v_max_f32_e32 v3, v3, v5
	v_mov_b32_e32 v5, v3
	v_mov_b32_e32 v6, v215
	s_waitcnt lgkmcnt(0)
; DI float wave_max(float v) { for (int o = 32; o >= 1; o >>= 1) v = fmaxf(v, shx(v, o)); return v; }
; DI void router_phase(const P& p, int l, int ntok, unsigned char* lds) {
;     ...
;       int se[4]; float sv[4];
; #pragma unroll
;       for (int k = 0; k < 4; ++k) {
;         float m = wave_max(v);
;         unsigned long long mask = __ballot(v == m);
;         int idx = __ffsll((long long)mask) - 1;
;         se[k] = idx & 31; sv[k] = m;
;         if (r == (idx & 31)) v = -3.0e38f;
;       }
;       float e1 = __expf(sv[1] - sv[0]), e2 = __expf(sv[2] - sv[0]), e3 = __expf(sv[3] - sv[0]);
;       float inv = 1.f / (1.f + e1 + e2 + e3);
;       if (valid && lane < 4) {
;         int e = lane == 0 ? se[0] : lane == 1 ? se[1] : lane == 2 ? se[2] : se[3];
;         float gt = (lane == 0 ? 1.f : lane == 1 ? e1 : lane == 2 ? e2 : e3) * inv;
;         int lp = atomicAdd(&lcnt[e], 1);
;         TOKE[tok * 4 + lane] = e; TOKG[tok * 4 + lane] = gt; TOKLP[tok * 4 + lane] = lp;
;       }
	v_max_f32_e32 v5, v5, v5
	v_lshlrev_b32_e32 v6, 2, v6
	v_bitop3_b32 v6, v6, 16, v220 bitop3:0x6c
	v_max_f32_e32 v3, v3, v5
	v_mov_b32_e32 v5, v3
	v_mov_b32_e32 v6, v215
	s_waitcnt lgkmcnt(0)
	v_max_f32_e32 v5, v5, v5
	v_lshlrev_b32_e32 v6, 2, v6
	v_bitop3_b32 v6, v6, 8, v220 bitop3:0x6c
	v_max_f32_e32 v3, v3, v5
	v_mov_b32_e32 v5, v3
	v_mov_b32_e32 v6, v215
	s_waitcnt lgkmcnt(0)
	v_max_f32_e32 v5, v5, v5
	v_lshlrev_b32_e32 v6, 2, v6
	v_bitop3_b32 v6, v6, 4, v220 bitop3:0x6c
	v_max_f32_e32 v3, v3, v5
	v_mov_b32_e32 v5, v3
	v_mov_b32_e32 v6, v215
	s_waitcnt lgkmcnt(0)
	v_max_f32_e32 v5, v5, v5
	v_max_f32_e32 v3, v3, v5
	v_cmp_eq_f32_e32 vcc, v4, v3
	s_ff1_i32_b64 s0, vcc
	s_and_b32 s0, s0, 31
	s_cmp_lg_u64 vcc, 0
	s_cselect_b32 s24, s0, 31
	v_lshlrev_b32_e32 v6, 2, v6
	v_cmp_ne_u32_e32 vcc, s24, v37
	v_bitop3_b32 v6, v6, s76, v220 bitop3:0x6c
	s_nop 0
	v_cndmask_b32_e32 v5, v223, v4, vcc
	s_nop 1
	v_max_f32_dpp v150, v5, v5 quad_perm:[1,0,3,2] row_mask:0xf bank_mask:0xf
	s_nop 1
	v_max_f32_dpp v150, v150, v150 quad_perm:[2,3,0,1] row_mask:0xf bank_mask:0xf
	s_nop 1
	v_max_f32_dpp v150, v150, v150 row_half_mirror row_mask:0xf bank_mask:0xf
	s_nop 1
	v_max_f32_dpp v150, v150, v150 row_mirror row_mask:0xf bank_mask:0xf
	s_nop 1
	v_max_f32_dpp v150, v150, v150 row_bcast:15 row_mask:0xa bank_mask:0xf
	s_nop 1
	v_max_f32_dpp v150, v150, v150 row_bcast:31 row_mask:0xc bank_mask:0xf
	s_nop 1
	v_readlane_b32 s32, v150, 63
	s_nop 1
	v_mov_b32_e32 v4, s32
	v_mov_b32_e32 v6, v215
	s_waitcnt lgkmcnt(0)
	v_max_f32_e32 v4, v4, v4
	v_lshlrev_b32_e32 v6, 2, v6
	v_bitop3_b32 v6, v6, 64, v220 bitop3:0x6c
	v_max_f32_e32 v4, v5, v4
	v_mov_b32_e32 v6, v4
	v_lshlrev_b32_e32 v7, 2, v7
	v_bitop3_b32 v7, v7, 32, v220 bitop3:0x6c
	s_waitcnt lgkmcnt(0)
	v_max_f32_e32 v6, v6, v6
	v_max_f32_e32 v4, v4, v6
	v_mov_b32_e32 v6, v4
	v_mov_b32_e32 v7, v215
	s_waitcnt lgkmcnt(0)
	v_max_f32_e32 v6, v6, v6
	v_lshlrev_b32_e32 v7, 2, v7
	v_bitop3_b32 v7, v7, 16, v220 bitop3:0x6c
	v_max_f32_e32 v4, v4, v6
	v_mov_b32_e32 v6, v4
	v_mov_b32_e32 v7, v215
	s_waitcnt lgkmcnt(0)
	v_max_f32_e32 v6, v6, v6
	v_lshlrev_b32_e32 v7, 2, v7
	v_bitop3_b32 v7, v7, 8, v220 bitop3:0x6c
	v_max_f32_e32 v4, v4, v6
	v_mov_b32_e32 v6, v4
	v_mov_b32_e32 v7, v215
	s_waitcnt lgkmcnt(0)
	v_max_f32_e32 v6, v6, v6
	v_lshlrev_b32_e32 v7, 2, v7
	v_bitop3_b32 v7, v7, 4, v220 bitop3:0x6c
	v_max_f32_e32 v4, v4, v6
	v_mov_b32_e32 v6, v4
	v_mov_b32_e32 v7, v215
	s_waitcnt lgkmcnt(0)
	v_max_f32_e32 v6, v6, v6
	v_max_f32_e32 v4, v4, v6
	v_cmp_eq_f32_e32 vcc, v5, v4
	s_ff1_i32_b64 s0, vcc
	s_and_b32 s0, s0, 31
	s_cmp_lg_u64 vcc, 0
	s_cselect_b32 s25, s0, 31
	v_lshlrev_b32_e32 v7, 2, v7
	v_cmp_ne_u32_e32 vcc, s25, v37
	v_bitop3_b32 v7, v7, s76, v220 bitop3:0x6c
	s_nop 0
	v_cndmask_b32_e32 v6, v223, v5, vcc
	s_nop 1
	v_max_f32_dpp v150, v6, v6 quad_perm:[1,0,3,2] row_mask:0xf bank_mask:0xf
	s_nop 1
	v_max_f32_dpp v150, v150, v150 quad_perm:[2,3,0,1] row_mask:0xf bank_mask:0xf
	s_nop 1
	v_max_f32_dpp v150, v150, v150 row_half_mirror row_mask:0xf bank_mask:0xf
	s_nop 1
	v_max_f32_dpp v150, v150, v150 row_mirror row_mask:0xf bank_mask:0xf
	s_nop 1
	v_max_f32_dpp v150, v150, v150 row_bcast:15 row_mask:0xa bank_mask:0xf
	s_nop 1
	v_max_f32_dpp v150, v150, v150 row_bcast:31 row_mask:0xc bank_mask:0xf
	s_nop 1
	v_readlane_b32 s32, v150, 63
	s_nop 1
	v_mov_b32_e32 v5, s32
	v_mov_b32_e32 v7, v215
	v_cmp_gt_i32_e32 vcc, s21, v39
	v_lshlrev_b32_e32 v7, 2, v7
	s_waitcnt lgkmcnt(0)
	v_max_f32_e32 v5, v5, v5
	v_bitop3_b32 v7, v7, 64, v220 bitop3:0x6c
	v_max_f32_e32 v5, v6, v5
	v_mov_b32_e32 v7, v5
	v_lshlrev_b32_e32 v8, 2, v8
	v_bitop3_b32 v8, v8, 32, v220 bitop3:0x6c
	s_and_b64 s[26:27], vcc, s[6:7]
	s_waitcnt lgkmcnt(0)
	v_max_f32_e32 v7, v7, v7
	v_max_f32_e32 v5, v5, v7
	v_mov_b32_e32 v7, v5
	v_mov_b32_e32 v8, v215
	s_waitcnt lgkmcnt(0)
	v_max_f32_e32 v7, v7, v7
	v_lshlrev_b32_e32 v8, 2, v8
	v_bitop3_b32 v8, v8, 16, v220 bitop3:0x6c
	v_max_f32_e32 v5, v5, v7
	v_mov_b32_e32 v7, v5
	v_mov_b32_e32 v8, v215
	s_waitcnt lgkmcnt(0)
	v_max_f32_e32 v7, v7, v7
	v_lshlrev_b32_e32 v8, 2, v8
	v_bitop3_b32 v8, v8, 8, v220 bitop3:0x6c
	v_max_f32_e32 v5, v5, v7
	v_mov_b32_e32 v7, v5
	v_mov_b32_e32 v8, v215
	s_waitcnt lgkmcnt(0)
	v_max_f32_e32 v7, v7, v7
	v_lshlrev_b32_e32 v8, 2, v8
	v_bitop3_b32 v8, v8, 4, v220 bitop3:0x6c
	v_max_f32_e32 v5, v5, v7
	v_mov_b32_e32 v7, v5
	s_waitcnt lgkmcnt(0)
	v_max_f32_e32 v7, v7, v7
	v_max_f32_e32 v5, v5, v7
	v_cmp_eq_f32_e64 s[0:1], v6, v5
	s_and_saveexec_b64 s[16:17], s[26:27]
	s_cbranch_execz .LBB0_1262
	v_sub_f32_e32 v5, v5, v2
	v_sub_f32_e32 v4, v4, v2
	v_sub_f32_e32 v2, v3, v2
	v_mul_f32_e32 v2, 0x3fb8aa3b, v2
	v_mul_f32_e32 v4, 0x3fb8aa3b, v4
	v_exp_f32_e32 v2, v2
	v_mul_f32_e32 v5, 0x3fb8aa3b, v5
	v_exp_f32_e32 v3, v4
	v_exp_f32_e32 v4, v5
	v_add_f32_e32 v5, 1.0, v2
	v_add_f32_e32 v5, v5, v3
	v_add_f32_e32 v5, v5, v4
	v_div_scale_f32 v6, s[26:27], v5, v5, 1.0
	v_rcp_f32_e32 v7, v6
	s_ff1_i32_b64 s26, s[0:1]
	s_and_b32 s26, s26, 31
	s_cmp_lg_u64 s[0:1], 0
	v_fma_f32 v8, -v6, v7, 1.0
	v_fmac_f32_e32 v7, v8, v7
	v_div_scale_f32 v8, vcc, 1.0, v5, 1.0
	v_mul_f32_e32 v9, v8, v7
	v_fma_f32 v10, -v6, v9, v8
	v_fmac_f32_e32 v9, v10, v7
	v_fma_f32 v6, -v6, v9, v8
	s_cselect_b32 s0, s26, 31
	v_div_fmas_f32 v6, v6, v7, v9
	v_mov_b32_e32 v7, s0
	v_mov_b32_e32 v8, s25
	v_cndmask_b32_e64 v7, v7, v8, s[12:13]
	v_mov_b32_e32 v8, s24
	v_cndmask_b32_e64 v3, v4, v3, s[12:13]
	v_cndmask_b32_e64 v7, v7, v8, s[10:11]
	v_mov_b32_e32 v8, s23
	v_cndmask_b32_e64 v2, v3, v2, s[10:11]
	v_div_fixup_f32 v5, v6, v5, 1.0
	v_cndmask_b32_e64 v7, v7, v8, s[8:9]
	v_cndmask_b32_e64 v2, v2, 1.0, s[8:9]
	v_mul_f32_e32 v8, v5, v2
	v_lshl_add_u32 v2, v7, 2, 0
	v_add_u32_e32 v6, s22, v39
	v_add_u32_e32 v2, 0x20080, v2
	ds_add_rtn_u32 v9, v2, v213
	v_lshl_or_b32 v2, v6, 2, v35
	v_ashrrev_i32_e32 v3, 31, v2
	v_readlane_b32 s0, v253, 30
	v_lshlrev_b64 v[2:3], 2, v[2:3]
	v_readlane_b32 s1, v253, 31
	s_nop 1
	v_lshl_add_u64 v[4:5], s[0:1], 0, v[2:3]
	v_readlane_b32 s0, v253, 32
	v_readlane_b32 s1, v253, 33
	global_store_dword v[4:5], v7, off
	s_nop 0
	v_lshl_add_u64 v[4:5], s[0:1], 0, v[2:3]
	v_readlane_b32 s0, v253, 34
	v_readlane_b32 s1, v253, 35
	global_store_dword v[4:5], v8, off
	s_nop 0
	v_lshl_add_u64 v[2:3], s[0:1], 0, v[2:3]
	s_waitcnt lgkmcnt(0)
	global_store_dword v[2:3], v9, off
; DI float wave_max(float v) { for (int o = 32; o >= 1; o >>= 1) v = fmaxf(v, shx(v, o)); return v; }
; DI void router_phase(const P& p, int l, int ntok, unsigned char* lds) {
;     ...
; #pragma unroll
;     for (int q = 0; q < 4; ++q) {
;       int tl = w * 4 + q;
;       int tok = tbase + c0 + tl;
;       bool valid = (c0 + tl) < per;
;       float v = br[r];
; #pragma unroll
;       for (int k = 0; k < 8; ++k) v += part[(k * 32 + tl) * 33 + r];
;       int se[4]; float sv[4];
; #pragma unroll
;       for (int k = 0; k < 4; ++k) {
;         float m = wave_max(v);
;         unsigned long long mask = __ballot(v == m);
;         int idx = __ffsll((long long)mask) - 1;
;         se[k] = idx & 31; sv[k] = m;
;         if (r == (idx & 31)) v = -3.0e38f;
;       }
;       float e1 = __expf(sv[1] - sv[0]), e2 = __expf(sv[2] - sv[0]), e3 = __expf(sv[3] - sv[0]);
.LBB0_1262:
	s_or_b64 exec, exec, s[16:17]
	global_load_dword v2, v[30:31], off
	ds_read_b32 v3, v74
	v_mov_b32_e32 v4, v215
	v_mov_b32_e32 v5, v215
	v_mov_b32_e32 v6, v215
	v_mov_b32_e32 v7, v215
	s_waitcnt vmcnt(0) lgkmcnt(0)
	v_add_f32_e32 v2, v2, v3
	ds_read_b32 v3, v73 offset:4356
	s_waitcnt lgkmcnt(0)
	v_add_f32_e32 v2, v2, v3
	ds_read_b32 v3, v73 offset:8580
	s_waitcnt lgkmcnt(0)
	v_add_f32_e32 v2, v2, v3
	ds_read_b32 v3, v73 offset:12804
	s_waitcnt lgkmcnt(0)
	v_add_f32_e32 v2, v2, v3
	ds_read_b32 v3, v73 offset:17028
	s_waitcnt lgkmcnt(0)
	v_add_f32_e32 v2, v2, v3
	ds_read_b32 v3, v73 offset:21252
	s_waitcnt lgkmcnt(0)
	v_add_f32_e32 v2, v2, v3
	ds_read_b32 v3, v73 offset:25476
	s_waitcnt lgkmcnt(0)
	v_add_f32_e32 v2, v2, v3
	ds_read_b32 v3, v73 offset:29700
	s_waitcnt lgkmcnt(0)
	v_add_f32_e32 v3, v2, v3
	v_mov_b32_e32 v2, v215
	s_nop 0
	v_lshlrev_b32_e32 v2, 2, v2
	v_bitop3_b32 v2, v2, s76, v220 bitop3:0x6c
	s_nop 1
	v_max_f32_dpp v150, v3, v3 quad_perm:[1,0,3,2] row_mask:0xf bank_mask:0xf
	s_nop 1
	v_max_f32_dpp v150, v150, v150 quad_perm:[2,3,0,1] row_mask:0xf bank_mask:0xf
	s_nop 1
	v_max_f32_dpp v150, v150, v150 row_half_mirror row_mask:0xf bank_mask:0xf
	s_nop 1
	v_max_f32_dpp v150, v150, v150 row_mirror row_mask:0xf bank_mask:0xf
	s_nop 1
	v_max_f32_dpp v150, v150, v150 row_bcast:15 row_mask:0xa bank_mask:0xf
	s_nop 1
	v_max_f32_dpp v150, v150, v150 row_bcast:31 row_mask:0xc bank_mask:0xf
	s_nop 1
	v_readlane_b32 s32, v150, 63
	s_nop 1
	v_mov_b32_e32 v2, s32
	v_lshlrev_b32_e32 v4, 2, v4
	v_bitop3_b32 v4, v4, 64, v220 bitop3:0x6c
	s_waitcnt lgkmcnt(0)
	v_max_f32_e32 v2, v2, v2
	v_max_f32_e32 v2, v3, v2
	v_mov_b32_e32 v4, v2
	s_waitcnt lgkmcnt(0)
	v_max_f32_e32 v4, v4, v4
	v_max_f32_e32 v2, v2, v4
	v_mov_b32_e32 v4, v215
	s_nop 0
	v_lshlrev_b32_e32 v4, 2, v4
	v_bitop3_b32 v4, v4, 32, v220 bitop3:0x6c
	v_mov_b32_e32 v4, v2
	s_waitcnt lgkmcnt(0)
	v_max_f32_e32 v4, v4, v4
	v_max_f32_e32 v2, v2, v4
	v_mov_b32_e32 v4, v215
	s_nop 0
	v_lshlrev_b32_e32 v4, 2, v4
	v_bitop3_b32 v4, v4, 16, v220 bitop3:0x6c
	v_mov_b32_e32 v4, v2
	s_waitcnt lgkmcnt(0)
	v_max_f32_e32 v4, v4, v4
	v_max_f32_e32 v2, v2, v4
	v_mov_b32_e32 v4, v215
	s_nop 0
	v_lshlrev_b32_e32 v4, 2, v4
	v_bitop3_b32 v4, v4, 8, v220 bitop3:0x6c
	v_mov_b32_e32 v4, v2
	s_waitcnt lgkmcnt(0)
	v_max_f32_e32 v4, v4, v4
	v_max_f32_e32 v2, v2, v4
	v_mov_b32_e32 v4, v215
	s_nop 0
	v_lshlrev_b32_e32 v4, 2, v4
	v_bitop3_b32 v4, v4, 4, v220 bitop3:0x6c
	v_mov_b32_e32 v4, v2
	s_waitcnt lgkmcnt(0)
	v_max_f32_e32 v4, v4, v4
	v_max_f32_e32 v2, v2, v4
	v_cmp_eq_f32_e32 vcc, v3, v2
	s_ff1_i32_b64 s0, vcc
	s_and_b32 s0, s0, 31
	s_cmp_lg_u64 vcc, 0
	s_cselect_b32 s23, s0, 31
	v_cmp_ne_u32_e32 vcc, s23, v37
	s_nop 1
	v_cndmask_b32_e32 v4, v223, v3, vcc
	v_mov_b32_e32 v3, v215
	s_nop 0
	v_lshlrev_b32_e32 v3, 2, v3
	v_bitop3_b32 v3, v3, s76, v220 bitop3:0x6c
	s_nop 1
	v_max_f32_dpp v150, v4, v4 quad_perm:[1,0,3,2] row_mask:0xf bank_mask:0xf
	s_nop 1
	v_max_f32_dpp v150, v150, v150 quad_perm:[2,3,0,1] row_mask:0xf bank_mask:0xf
	s_nop 1
	v_max_f32_dpp v150, v150, v150 row_half_mirror row_mask:0xf bank_mask:0xf
	s_nop 1
	v_max_f32_dpp v150, v150, v150 row_mirror row_mask:0xf bank_mask:0xf
	s_nop 1
	v_max_f32_dpp v150, v150, v150 row_bcast:15 row_mask:0xa bank_mask:0xf
	s_nop 1
	v_max_f32_dpp v150, v150, v150 row_bcast:31 row_mask:0xc bank_mask:0xf
	s_nop 1
	v_readlane_b32 s32, v150, 63
	s_nop 1
	v_mov_b32_e32 v3, s32
	v_lshlrev_b32_e32 v5, 2, v5
	v_bitop3_b32 v5, v5, 64, v220 bitop3:0x6c
	s_waitcnt lgkmcnt(0)
	v_max_f32_e32 v3, v3, v3
	v_max_f32_e32 v3, v4, v3
	v_mov_b32_e32 v5, v3
	s_waitcnt lgkmcnt(0)
	v_max_f32_e32 v5, v5, v5
	v_max_f32_e32 v3, v3, v5
	v_mov_b32_e32 v5, v215
	s_nop 0
	v_lshlrev_b32_e32 v5, 2, v5
	v_bitop3_b32 v5, v5, 32, v220 bitop3:0x6c
	v_mov_b32_e32 v5, v3
	s_waitcnt lgkmcnt(0)
	v_max_f32_e32 v5, v5, v5
	v_max_f32_e32 v3, v3, v5
	v_mov_b32_e32 v5, v215
	s_nop 0
	v_lshlrev_b32_e32 v5, 2, v5
	v_bitop3_b32 v5, v5, 16, v220 bitop3:0x6c
	v_mov_b32_e32 v5, v3
	s_waitcnt lgkmcnt(0)
	v_max_f32_e32 v5, v5, v5
	v_max_f32_e32 v3, v3, v5
	v_mov_b32_e32 v5, v215
	s_nop 0
	v_lshlrev_b32_e32 v5, 2, v5
	v_bitop3_b32 v5, v5, 8, v220 bitop3:0x6c
	v_mov_b32_e32 v5, v3
	s_waitcnt lgkmcnt(0)
	v_max_f32_e32 v5, v5, v5
	v_max_f32_e32 v3, v3, v5
	v_mov_b32_e32 v5, v215
	s_nop 0
	v_lshlrev_b32_e32 v5, 2, v5
	v_bitop3_b32 v5, v5, 4, v220 bitop3:0x6c
	v_mov_b32_e32 v5, v3
	s_waitcnt lgkmcnt(0)
	v_max_f32_e32 v5, v5, v5
	v_max_f32_e32 v3, v3, v5
	v_cmp_eq_f32_e32 vcc, v4, v3
	s_ff1_i32_b64 s0, vcc
	s_and_b32 s0, s0, 31
	s_cmp_lg_u64 vcc, 0
	s_cselect_b32 s24, s0, 31
	v_cmp_ne_u32_e32 vcc, s24, v37
	s_nop 1
	v_cndmask_b32_e32 v5, v223, v4, vcc
	v_mov_b32_e32 v4, v215
	s_nop 0
	v_lshlrev_b32_e32 v4, 2, v4
	v_bitop3_b32 v4, v4, s76, v220 bitop3:0x6c
	s_nop 1
	v_max_f32_dpp v150, v5, v5 quad_perm:[1,0,3,2] row_mask:0xf bank_mask:0xf
	s_nop 1
	v_max_f32_dpp v150, v150, v150 quad_perm:[2,3,0,1] row_mask:0xf bank_mask:0xf
	s_nop 1
	v_max_f32_dpp v150, v150, v150 row_half_mirror row_mask:0xf bank_mask:0xf
	s_nop 1
	v_max_f32_dpp v150, v150, v150 row_mirror row_mask:0xf bank_mask:0xf
	s_nop 1
	v_max_f32_dpp v150, v150, v150 row_bcast:15 row_mask:0xa bank_mask:0xf
	s_nop 1
	v_max_f32_dpp v150, v150, v150 row_bcast:31 row_mask:0xc bank_mask:0xf
	s_nop 1
	v_readlane_b32 s32, v150, 63
	s_nop 1
	v_mov_b32_e32 v4, s32
	v_lshlrev_b32_e32 v6, 2, v6
	v_bitop3_b32 v6, v6, 64, v220 bitop3:0x6c
	s_waitcnt lgkmcnt(0)
	v_max_f32_e32 v4, v4, v4
	v_max_f32_e32 v4, v5, v4
	v_mov_b32_e32 v6, v4
	s_waitcnt lgkmcnt(0)
	v_max_f32_e32 v6, v6, v6
	v_max_f32_e32 v4, v4, v6
	v_mov_b32_e32 v6, v215
	s_nop 0
	v_lshlrev_b32_e32 v6, 2, v6
	v_bitop3_b32 v6, v6, 32, v220 bitop3:0x6c
	v_mov_b32_e32 v6, v4
	s_waitcnt lgkmcnt(0)
; DI float wave_max(float v) { for (int o = 32; o >= 1; o >>= 1) v = fmaxf(v, shx(v, o)); return v; }
; DI void router_phase(const P& p, int l, int ntok, unsigned char* lds) {
;     ...
;       int se[4]; float sv[4];
; #pragma unroll
;       for (int k = 0; k < 4; ++k) {
;         float m = wave_max(v);
;         unsigned long long mask = __ballot(v == m);
;         int idx = __ffsll((long long)mask) - 1;
;         se[k] = idx & 31; sv[k] = m;
;         if (r == (idx & 31)) v = -3.0e38f;
;       }
;       float e1 = __expf(sv[1] - sv[0]), e2 = __expf(sv[2] - sv[0]), e3 = __expf(sv[3] - sv[0]);
;       float inv = 1.f / (1.f + e1 + e2 + e3);
;       if (valid && lane < 4) {
;         int e = lane == 0 ? se[0] : lane == 1 ? se[1] : lane == 2 ? se[2] : se[3];
;         float gt = (lane == 0 ? 1.f : lane == 1 ? e1 : lane == 2 ? e2 : e3) * inv;
;         int lp = atomicAdd(&lcnt[e], 1);
;         TOKE[tok * 4 + lane] = e; TOKG[tok * 4 + lane] = gt; TOKLP[tok * 4 + lane] = lp;
;       }
	v_max_f32_e32 v6, v6, v6
	v_max_f32_e32 v4, v4, v6
	v_mov_b32_e32 v6, v215
	s_nop 0
	v_lshlrev_b32_e32 v6, 2, v6
	v_bitop3_b32 v6, v6, 16, v220 bitop3:0x6c
	v_mov_b32_e32 v6, v4
	s_waitcnt lgkmcnt(0)
	v_max_f32_e32 v6, v6, v6
	v_max_f32_e32 v4, v4, v6
	v_mov_b32_e32 v6, v215
	s_nop 0
	v_lshlrev_b32_e32 v6, 2, v6
	v_bitop3_b32 v6, v6, 8, v220 bitop3:0x6c
	v_mov_b32_e32 v6, v4
	s_waitcnt lgkmcnt(0)
	v_max_f32_e32 v6, v6, v6
	v_max_f32_e32 v4, v4, v6
	v_mov_b32_e32 v6, v215
	s_nop 0
	v_lshlrev_b32_e32 v6, 2, v6
	v_bitop3_b32 v6, v6, 4, v220 bitop3:0x6c
	v_mov_b32_e32 v6, v4
	s_waitcnt lgkmcnt(0)
	v_max_f32_e32 v6, v6, v6
	v_max_f32_e32 v4, v4, v6
	v_cmp_eq_f32_e32 vcc, v5, v4
	s_ff1_i32_b64 s0, vcc
	s_and_b32 s0, s0, 31
	s_cmp_lg_u64 vcc, 0
	s_cselect_b32 s25, s0, 31
	v_cmp_ne_u32_e32 vcc, s25, v37
	s_nop 1
	v_cndmask_b32_e32 v6, v223, v5, vcc
	v_mov_b32_e32 v5, v215
	v_cmp_gt_i32_e32 vcc, s21, v43
	v_lshlrev_b32_e32 v5, 2, v5
	v_bitop3_b32 v5, v5, s76, v220 bitop3:0x6c
	s_nop 1
	v_max_f32_dpp v150, v6, v6 quad_perm:[1,0,3,2] row_mask:0xf bank_mask:0xf
	s_nop 1
	v_max_f32_dpp v150, v150, v150 quad_perm:[2,3,0,1] row_mask:0xf bank_mask:0xf
	s_nop 1
	v_max_f32_dpp v150, v150, v150 row_half_mirror row_mask:0xf bank_mask:0xf
	s_nop 1
	v_max_f32_dpp v150, v150, v150 row_mirror row_mask:0xf bank_mask:0xf
	s_nop 1
	v_max_f32_dpp v150, v150, v150 row_bcast:15 row_mask:0xa bank_mask:0xf
	s_nop 1
	v_max_f32_dpp v150, v150, v150 row_bcast:31 row_mask:0xc bank_mask:0xf
	s_nop 1
	v_readlane_b32 s32, v150, 63
	s_nop 1
	v_mov_b32_e32 v5, s32
	v_lshlrev_b32_e32 v7, 2, v7
	v_bitop3_b32 v7, v7, 64, v220 bitop3:0x6c
	s_and_b64 s[26:27], vcc, s[6:7]
	s_waitcnt lgkmcnt(0)
	v_max_f32_e32 v5, v5, v5
	v_max_f32_e32 v5, v6, v5
	v_mov_b32_e32 v7, v5
	s_waitcnt lgkmcnt(0)
	v_max_f32_e32 v7, v7, v7
	v_max_f32_e32 v5, v5, v7
	v_mov_b32_e32 v7, v215
	s_nop 0
	v_lshlrev_b32_e32 v7, 2, v7
	v_bitop3_b32 v7, v7, 32, v220 bitop3:0x6c
	v_mov_b32_e32 v7, v5
	s_waitcnt lgkmcnt(0)
	v_max_f32_e32 v7, v7, v7
	v_max_f32_e32 v5, v5, v7
	v_mov_b32_e32 v7, v215
	s_nop 0
	v_lshlrev_b32_e32 v7, 2, v7
	v_bitop3_b32 v7, v7, 16, v220 bitop3:0x6c
	v_mov_b32_e32 v7, v5
	s_waitcnt lgkmcnt(0)
	v_max_f32_e32 v7, v7, v7
	v_max_f32_e32 v5, v5, v7
	v_mov_b32_e32 v7, v215
	s_nop 0
	v_lshlrev_b32_e32 v7, 2, v7
	v_bitop3_b32 v7, v7, 8, v220 bitop3:0x6c
	v_mov_b32_e32 v7, v5
	s_waitcnt lgkmcnt(0)
	v_max_f32_e32 v7, v7, v7
	v_max_f32_e32 v5, v5, v7
	v_mov_b32_e32 v7, v215
	s_nop 0
	v_lshlrev_b32_e32 v7, 2, v7
	v_bitop3_b32 v7, v7, 4, v220 bitop3:0x6c
	v_mov_b32_e32 v7, v5
	s_waitcnt lgkmcnt(0)
	v_max_f32_e32 v7, v7, v7
	v_max_f32_e32 v5, v5, v7
	v_cmp_eq_f32_e64 s[0:1], v6, v5
	s_and_saveexec_b64 s[16:17], s[26:27]
	s_cbranch_execz .LBB0_1264
	v_sub_f32_e32 v5, v5, v2
	v_sub_f32_e32 v4, v4, v2
	v_sub_f32_e32 v2, v3, v2
	v_mul_f32_e32 v2, 0x3fb8aa3b, v2
	v_mul_f32_e32 v4, 0x3fb8aa3b, v4
	v_exp_f32_e32 v2, v2
	v_mul_f32_e32 v5, 0x3fb8aa3b, v5
	v_exp_f32_e32 v3, v4
	v_exp_f32_e32 v4, v5
	v_add_f32_e32 v5, 1.0, v2
	v_add_f32_e32 v5, v5, v3
	v_add_f32_e32 v5, v5, v4
	v_div_scale_f32 v6, s[26:27], v5, v5, 1.0
	v_rcp_f32_e32 v7, v6
	s_ff1_i32_b64 s26, s[0:1]
	s_and_b32 s26, s26, 31
	s_cmp_lg_u64 s[0:1], 0
	v_fma_f32 v8, -v6, v7, 1.0
	v_fmac_f32_e32 v7, v8, v7
	v_div_scale_f32 v8, vcc, 1.0, v5, 1.0
	v_mul_f32_e32 v9, v8, v7
	v_fma_f32 v10, -v6, v9, v8
	v_fmac_f32_e32 v9, v10, v7
	v_fma_f32 v6, -v6, v9, v8
	s_cselect_b32 s0, s26, 31
	v_div_fmas_f32 v6, v6, v7, v9
	v_mov_b32_e32 v7, s0
	v_mov_b32_e32 v8, s25
	v_cndmask_b32_e64 v7, v7, v8, s[12:13]
	v_mov_b32_e32 v8, s24
	v_cndmask_b32_e64 v3, v4, v3, s[12:13]
	v_cndmask_b32_e64 v7, v7, v8, s[10:11]
	v_mov_b32_e32 v8, s23
	v_cndmask_b32_e64 v2, v3, v2, s[10:11]
	v_div_fixup_f32 v5, v6, v5, 1.0
	v_cndmask_b32_e64 v7, v7, v8, s[8:9]
	v_cndmask_b32_e64 v2, v2, 1.0, s[8:9]
	v_mul_f32_e32 v8, v5, v2
	v_lshl_add_u32 v2, v7, 2, 0
	v_add_u32_e32 v6, s22, v43
	v_add_u32_e32 v2, 0x20080, v2
	ds_add_rtn_u32 v9, v2, v213
	v_lshl_or_b32 v2, v6, 2, v35
	v_ashrrev_i32_e32 v3, 31, v2
	v_readlane_b32 s0, v253, 30
	v_lshlrev_b64 v[2:3], 2, v[2:3]
	v_readlane_b32 s1, v253, 31
	s_nop 1
	v_lshl_add_u64 v[4:5], s[0:1], 0, v[2:3]
	v_readlane_b32 s0, v253, 32
	v_readlane_b32 s1, v253, 33
	global_store_dword v[4:5], v7, off
	s_nop 0
	v_lshl_add_u64 v[4:5], s[0:1], 0, v[2:3]
	v_readlane_b32 s0, v253, 34
	v_readlane_b32 s1, v253, 35
	global_store_dword v[4:5], v8, off
	s_nop 0
	v_lshl_add_u64 v[2:3], s[0:1], 0, v[2:3]
	s_waitcnt lgkmcnt(0)
	global_store_dword v[2:3], v9, off
; DI float wave_max(float v) { for (int o = 32; o >= 1; o >>= 1) v = fmaxf(v, shx(v, o)); return v; }
; DI void router_phase(const P& p, int l, int ntok, unsigned char* lds) {
;     ...
; #pragma unroll
;     for (int q = 0; q < 4; ++q) {
;       int tl = w * 4 + q;
;       int tok = tbase + c0 + tl;
;       bool valid = (c0 + tl) < per;
;       float v = br[r];
; #pragma unroll
;       for (int k = 0; k < 8; ++k) v += part[(k * 32 + tl) * 33 + r];
;       int se[4]; float sv[4];
; #pragma unroll
;       for (int k = 0; k < 4; ++k) {
;         float m = wave_max(v);
;         unsigned long long mask = __ballot(v == m);
;         int idx = __ffsll((long long)mask) - 1;
;         se[k] = idx & 31; sv[k] = m;
;         if (r == (idx & 31)) v = -3.0e38f;
;       }
;       float e1 = __expf(sv[1] - sv[0]), e2 = __expf(sv[2] - sv[0]), e3 = __expf(sv[3] - sv[0]);
.LBB0_1264:
	s_or_b64 exec, exec, s[16:17]
	global_load_dword v2, v[30:31], off
	ds_read_b32 v3, v74 offset:132
	v_mov_b32_e32 v4, v215
	v_mov_b32_e32 v5, v215
	v_mov_b32_e32 v6, v215
	v_mov_b32_e32 v7, v215
	s_waitcnt vmcnt(0) lgkmcnt(0)
	v_add_f32_e32 v2, v2, v3
	ds_read_b32 v3, v73 offset:4488
	s_waitcnt lgkmcnt(0)
	v_add_f32_e32 v2, v2, v3
	ds_read_b32 v3, v73 offset:8712
	s_waitcnt lgkmcnt(0)
	v_add_f32_e32 v2, v2, v3
	ds_read_b32 v3, v73 offset:12936
	s_waitcnt lgkmcnt(0)
	v_add_f32_e32 v2, v2, v3
	ds_read_b32 v3, v73 offset:17160
	s_waitcnt lgkmcnt(0)
	v_add_f32_e32 v2, v2, v3
	ds_read_b32 v3, v73 offset:21384
	s_waitcnt lgkmcnt(0)
	v_add_f32_e32 v2, v2, v3
	ds_read_b32 v3, v73 offset:25608
	s_waitcnt lgkmcnt(0)
	v_add_f32_e32 v2, v2, v3
	ds_read_b32 v3, v73 offset:29832
	s_waitcnt lgkmcnt(0)
	v_add_f32_e32 v3, v2, v3
	v_mov_b32_e32 v2, v215
	s_nop 0
	v_lshlrev_b32_e32 v2, 2, v2
	v_bitop3_b32 v2, v2, s76, v220 bitop3:0x6c
	s_nop 1
	v_max_f32_dpp v150, v3, v3 quad_perm:[1,0,3,2] row_mask:0xf bank_mask:0xf
	s_nop 1
	v_max_f32_dpp v150, v150, v150 quad_perm:[2,3,0,1] row_mask:0xf bank_mask:0xf
	s_nop 1
	v_max_f32_dpp v150, v150, v150 row_half_mirror row_mask:0xf bank_mask:0xf
	s_nop 1
	v_max_f32_dpp v150, v150, v150 row_mirror row_mask:0xf bank_mask:0xf
	s_nop 1
	v_max_f32_dpp v150, v150, v150 row_bcast:15 row_mask:0xa bank_mask:0xf
	s_nop 1
	v_max_f32_dpp v150, v150, v150 row_bcast:31 row_mask:0xc bank_mask:0xf
	s_nop 1
	v_readlane_b32 s32, v150, 63
	s_nop 1
	v_mov_b32_e32 v2, s32
	v_lshlrev_b32_e32 v4, 2, v4
	v_bitop3_b32 v4, v4, 64, v220 bitop3:0x6c
	s_waitcnt lgkmcnt(0)
	v_max_f32_e32 v2, v2, v2
	v_max_f32_e32 v2, v3, v2
	v_mov_b32_e32 v4, v2
	s_waitcnt lgkmcnt(0)
	v_max_f32_e32 v4, v4, v4
	v_max_f32_e32 v2, v2, v4
	v_mov_b32_e32 v4, v215
	s_nop 0
	v_lshlrev_b32_e32 v4, 2, v4
	v_bitop3_b32 v4, v4, 32, v220 bitop3:0x6c
	v_mov_b32_e32 v4, v2
	s_waitcnt lgkmcnt(0)
	v_max_f32_e32 v4, v4, v4
	v_max_f32_e32 v2, v2, v4
	v_mov_b32_e32 v4, v215
	s_nop 0
	v_lshlrev_b32_e32 v4, 2, v4
	v_bitop3_b32 v4, v4, 16, v220 bitop3:0x6c
	v_mov_b32_e32 v4, v2
	s_waitcnt lgkmcnt(0)
	v_max_f32_e32 v4, v4, v4
	v_max_f32_e32 v2, v2, v4
	v_mov_b32_e32 v4, v215
	s_nop 0
	v_lshlrev_b32_e32 v4, 2, v4
	v_bitop3_b32 v4, v4, 8, v220 bitop3:0x6c
	v_mov_b32_e32 v4, v2
	s_waitcnt lgkmcnt(0)
	v_max_f32_e32 v4, v4, v4
	v_max_f32_e32 v2, v2, v4
	v_mov_b32_e32 v4, v215
	s_nop 0
	v_lshlrev_b32_e32 v4, 2, v4
	v_bitop3_b32 v4, v4, 4, v220 bitop3:0x6c
	v_mov_b32_e32 v4, v2
	s_waitcnt lgkmcnt(0)
	v_max_f32_e32 v4, v4, v4
	v_max_f32_e32 v2, v2, v4
	v_cmp_eq_f32_e32 vcc, v3, v2
	s_ff1_i32_b64 s0, vcc
	s_and_b32 s0, s0, 31
	s_cmp_lg_u64 vcc, 0
	s_cselect_b32 s23, s0, 31
	v_cmp_ne_u32_e32 vcc, s23, v37
	s_nop 1
	v_cndmask_b32_e32 v4, v223, v3, vcc
	v_mov_b32_e32 v3, v215
	s_nop 0
	v_lshlrev_b32_e32 v3, 2, v3
	v_bitop3_b32 v3, v3, s76, v220 bitop3:0x6c
	s_nop 1
	v_max_f32_dpp v150, v4, v4 quad_perm:[1,0,3,2] row_mask:0xf bank_mask:0xf
	s_nop 1
	v_max_f32_dpp v150, v150, v150 quad_perm:[2,3,0,1] row_mask:0xf bank_mask:0xf
	s_nop 1
	v_max_f32_dpp v150, v150, v150 row_half_mirror row_mask:0xf bank_mask:0xf
	s_nop 1
	v_max_f32_dpp v150, v150, v150 row_mirror row_mask:0xf bank_mask:0xf
	s_nop 1
	v_max_f32_dpp v150, v150, v150 row_bcast:15 row_mask:0xa bank_mask:0xf
	s_nop 1
	v_max_f32_dpp v150, v150, v150 row_bcast:31 row_mask:0xc bank_mask:0xf
	s_nop 1
	v_readlane_b32 s32, v150, 63
	s_nop 1
	v_mov_b32_e32 v3, s32
	v_lshlrev_b32_e32 v5, 2, v5
	v_bitop3_b32 v5, v5, 64, v220 bitop3:0x6c
	s_waitcnt lgkmcnt(0)
	v_max_f32_e32 v3, v3, v3
	v_max_f32_e32 v3, v4, v3
	v_mov_b32_e32 v5, v3
	s_waitcnt lgkmcnt(0)
	v_max_f32_e32 v5, v5, v5
	v_max_f32_e32 v3, v3, v5
	v_mov_b32_e32 v5, v215
	s_nop 0
	v_lshlrev_b32_e32 v5, 2, v5
	v_bitop3_b32 v5, v5, 32, v220 bitop3:0x6c
	v_mov_b32_e32 v5, v3
	s_waitcnt lgkmcnt(0)
	v_max_f32_e32 v5, v5, v5
	v_max_f32_e32 v3, v3, v5
	v_mov_b32_e32 v5, v215
	s_nop 0
	v_lshlrev_b32_e32 v5, 2, v5
	v_bitop3_b32 v5, v5, 16, v220 bitop3:0x6c
	v_mov_b32_e32 v5, v3
	s_waitcnt lgkmcnt(0)
	v_max_f32_e32 v5, v5, v5
	v_max_f32_e32 v3, v3, v5
	v_mov_b32_e32 v5, v215
	s_nop 0
	v_lshlrev_b32_e32 v5, 2, v5
	v_bitop3_b32 v5, v5, 8, v220 bitop3:0x6c
	v_mov_b32_e32 v5, v3
	s_waitcnt lgkmcnt(0)
	v_max_f32_e32 v5, v5, v5
	v_max_f32_e32 v3, v3, v5
	v_mov_b32_e32 v5, v215
	s_nop 0
	v_lshlrev_b32_e32 v5, 2, v5
	v_bitop3_b32 v5, v5, 4, v220 bitop3:0x6c
	v_mov_b32_e32 v5, v3
	s_waitcnt lgkmcnt(0)
	v_max_f32_e32 v5, v5, v5
	v_max_f32_e32 v3, v3, v5
	v_cmp_eq_f32_e32 vcc, v4, v3
	s_ff1_i32_b64 s0, vcc
	s_and_b32 s0, s0, 31
	s_cmp_lg_u64 vcc, 0
	s_cselect_b32 s24, s0, 31
	v_cmp_ne_u32_e32 vcc, s24, v37
	s_nop 1
	v_cndmask_b32_e32 v5, v223, v4, vcc
	v_mov_b32_e32 v4, v215
	s_nop 0
	v_lshlrev_b32_e32 v4, 2, v4
	v_bitop3_b32 v4, v4, s76, v220 bitop3:0x6c
	s_nop 1
	v_max_f32_dpp v150, v5, v5 quad_perm:[1,0,3,2] row_mask:0xf bank_mask:0xf
	s_nop 1
	v_max_f32_dpp v150, v150, v150 quad_perm:[2,3,0,1] row_mask:0xf bank_mask:0xf
	s_nop 1
	v_max_f32_dpp v150, v150, v150 row_half_mirror row_mask:0xf bank_mask:0xf
	s_nop 1
	v_max_f32_dpp v150, v150, v150 row_mirror row_mask:0xf bank_mask:0xf
	s_nop 1
	v_max_f32_dpp v150, v150, v150 row_bcast:15 row_mask:0xa bank_mask:0xf
	s_nop 1
	v_max_f32_dpp v150, v150, v150 row_bcast:31 row_mask:0xc bank_mask:0xf
	s_nop 1
	v_readlane_b32 s32, v150, 63
	s_nop 1
	v_mov_b32_e32 v4, s32
	v_lshlrev_b32_e32 v6, 2, v6
	v_bitop3_b32 v6, v6, 64, v220 bitop3:0x6c
	s_waitcnt lgkmcnt(0)
	v_max_f32_e32 v4, v4, v4
	v_max_f32_e32 v4, v5, v4
	v_mov_b32_e32 v6, v4
	s_waitcnt lgkmcnt(0)
	v_max_f32_e32 v6, v6, v6
	v_max_f32_e32 v4, v4, v6
	v_mov_b32_e32 v6, v215
	s_nop 0
	v_lshlrev_b32_e32 v6, 2, v6
	v_bitop3_b32 v6, v6, 32, v220 bitop3:0x6c
	v_mov_b32_e32 v6, v4
	s_waitcnt lgkmcnt(0)
; DI float wave_max(float v) { for (int o = 32; o >= 1; o >>= 1) v = fmaxf(v, shx(v, o)); return v; }
; DI void router_phase(const P& p, int l, int ntok, unsigned char* lds) {
;     ...
;       int se[4]; float sv[4];
; #pragma unroll
;       for (int k = 0; k < 4; ++k) {
;         float m = wave_max(v);
;         unsigned long long mask = __ballot(v == m);
;         int idx = __ffsll((long long)mask) - 1;
;         se[k] = idx & 31; sv[k] = m;
;         if (r == (idx & 31)) v = -3.0e38f;
;       }
;       float e1 = __expf(sv[1] - sv[0]), e2 = __expf(sv[2] - sv[0]), e3 = __expf(sv[3] - sv[0]);
;       float inv = 1.f / (1.f + e1 + e2 + e3);
;       if (valid && lane < 4) {
;         int e = lane == 0 ? se[0] : lane == 1 ? se[1] : lane == 2 ? se[2] : se[3];
;         float gt = (lane == 0 ? 1.f : lane == 1 ? e1 : lane == 2 ? e2 : e3) * inv;
;         int lp = atomicAdd(&lcnt[e], 1);
;         TOKE[tok * 4 + lane] = e; TOKG[tok * 4 + lane] = gt; TOKLP[tok * 4 + lane] = lp;
;       }
	v_max_f32_e32 v6, v6, v6
	v_max_f32_e32 v4, v4, v6
	v_mov_b32_e32 v6, v215
	s_nop 0
	v_lshlrev_b32_e32 v6, 2, v6
	v_bitop3_b32 v6, v6, 16, v220 bitop3:0x6c
	v_mov_b32_e32 v6, v4
	s_waitcnt lgkmcnt(0)
	v_max_f32_e32 v6, v6, v6
	v_max_f32_e32 v4, v4, v6
	v_mov_b32_e32 v6, v215
	s_nop 0
	v_lshlrev_b32_e32 v6, 2, v6
	v_bitop3_b32 v6, v6, 8, v220 bitop3:0x6c
	v_mov_b32_e32 v6, v4
	s_waitcnt lgkmcnt(0)
	v_max_f32_e32 v6, v6, v6
	v_max_f32_e32 v4, v4, v6
	v_mov_b32_e32 v6, v215
	s_nop 0
	v_lshlrev_b32_e32 v6, 2, v6
	v_bitop3_b32 v6, v6, 4, v220 bitop3:0x6c
	v_mov_b32_e32 v6, v4
	s_waitcnt lgkmcnt(0)
	v_max_f32_e32 v6, v6, v6
	v_max_f32_e32 v4, v4, v6
	v_cmp_eq_f32_e32 vcc, v5, v4
	s_ff1_i32_b64 s0, vcc
	s_and_b32 s0, s0, 31
	s_cmp_lg_u64 vcc, 0
	s_cselect_b32 s25, s0, 31
	v_cmp_ne_u32_e32 vcc, s25, v37
	s_nop 1
	v_cndmask_b32_e32 v6, v223, v5, vcc
	v_mov_b32_e32 v5, v215
	v_cmp_gt_i32_e32 vcc, s21, v45
	v_lshlrev_b32_e32 v5, 2, v5
	v_bitop3_b32 v5, v5, s76, v220 bitop3:0x6c
	s_nop 1
	v_max_f32_dpp v150, v6, v6 quad_perm:[1,0,3,2] row_mask:0xf bank_mask:0xf
	s_nop 1
	v_max_f32_dpp v150, v150, v150 quad_perm:[2,3,0,1] row_mask:0xf bank_mask:0xf
	s_nop 1
	v_max_f32_dpp v150, v150, v150 row_half_mirror row_mask:0xf bank_mask:0xf
	s_nop 1
	v_max_f32_dpp v150, v150, v150 row_mirror row_mask:0xf bank_mask:0xf
	s_nop 1
	v_max_f32_dpp v150, v150, v150 row_bcast:15 row_mask:0xa bank_mask:0xf
	s_nop 1
	v_max_f32_dpp v150, v150, v150 row_bcast:31 row_mask:0xc bank_mask:0xf
	s_nop 1
	v_readlane_b32 s32, v150, 63
	s_nop 1
	v_mov_b32_e32 v5, s32
	v_lshlrev_b32_e32 v7, 2, v7
	v_bitop3_b32 v7, v7, 64, v220 bitop3:0x6c
	s_and_b64 s[26:27], vcc, s[6:7]
	s_waitcnt lgkmcnt(0)
	v_max_f32_e32 v5, v5, v5
	v_max_f32_e32 v5, v6, v5
	v_mov_b32_e32 v7, v5
	s_waitcnt lgkmcnt(0)
	v_max_f32_e32 v7, v7, v7
	v_max_f32_e32 v5, v5, v7
	v_mov_b32_e32 v7, v215
	s_nop 0
	v_lshlrev_b32_e32 v7, 2, v7
	v_bitop3_b32 v7, v7, 32, v220 bitop3:0x6c
	v_mov_b32_e32 v7, v5
	s_waitcnt lgkmcnt(0)
	v_max_f32_e32 v7, v7, v7
	v_max_f32_e32 v5, v5, v7
	v_mov_b32_e32 v7, v215
	s_nop 0
	v_lshlrev_b32_e32 v7, 2, v7
	v_bitop3_b32 v7, v7, 16, v220 bitop3:0x6c
	v_mov_b32_e32 v7, v5
	s_waitcnt lgkmcnt(0)
	v_max_f32_e32 v7, v7, v7
	v_max_f32_e32 v5, v5, v7
	v_mov_b32_e32 v7, v215
	s_nop 0
	v_lshlrev_b32_e32 v7, 2, v7
	v_bitop3_b32 v7, v7, 8, v220 bitop3:0x6c
	v_mov_b32_e32 v7, v5
	s_waitcnt lgkmcnt(0)
	v_max_f32_e32 v7, v7, v7
	v_max_f32_e32 v5, v5, v7
	v_mov_b32_e32 v7, v215
	s_nop 0
	v_lshlrev_b32_e32 v7, 2, v7
	v_bitop3_b32 v7, v7, 4, v220 bitop3:0x6c
	v_mov_b32_e32 v7, v5
	s_waitcnt lgkmcnt(0)
	v_max_f32_e32 v7, v7, v7
	v_max_f32_e32 v5, v5, v7
	v_cmp_eq_f32_e64 s[0:1], v6, v5
	s_and_saveexec_b64 s[16:17], s[26:27]
	s_cbranch_execz .LBB0_1266
	v_sub_f32_e32 v5, v5, v2
	v_sub_f32_e32 v4, v4, v2
	v_sub_f32_e32 v2, v3, v2
	v_mul_f32_e32 v2, 0x3fb8aa3b, v2
	v_mul_f32_e32 v4, 0x3fb8aa3b, v4
	v_exp_f32_e32 v2, v2
	v_mul_f32_e32 v5, 0x3fb8aa3b, v5
	v_exp_f32_e32 v3, v4
	v_exp_f32_e32 v4, v5
	v_add_f32_e32 v5, 1.0, v2
	v_add_f32_e32 v5, v5, v3
	v_add_f32_e32 v5, v5, v4
	v_div_scale_f32 v6, s[26:27], v5, v5, 1.0
	v_rcp_f32_e32 v7, v6
	s_ff1_i32_b64 s26, s[0:1]
	s_and_b32 s26, s26, 31
	s_cmp_lg_u64 s[0:1], 0
	v_fma_f32 v8, -v6, v7, 1.0
	v_fmac_f32_e32 v7, v8, v7
	v_div_scale_f32 v8, vcc, 1.0, v5, 1.0
	v_mul_f32_e32 v9, v8, v7
	v_fma_f32 v10, -v6, v9, v8
	v_fmac_f32_e32 v9, v10, v7
	v_fma_f32 v6, -v6, v9, v8
	s_cselect_b32 s0, s26, 31
	v_div_fmas_f32 v6, v6, v7, v9
	v_mov_b32_e32 v7, s0
	v_mov_b32_e32 v8, s25
	v_cndmask_b32_e64 v7, v7, v8, s[12:13]
	v_mov_b32_e32 v8, s24
	v_cndmask_b32_e64 v3, v4, v3, s[12:13]
	v_cndmask_b32_e64 v7, v7, v8, s[10:11]
	v_mov_b32_e32 v8, s23
	v_cndmask_b32_e64 v2, v3, v2, s[10:11]
	v_div_fixup_f32 v5, v6, v5, 1.0
	v_cndmask_b32_e64 v7, v7, v8, s[8:9]
	v_cndmask_b32_e64 v2, v2, 1.0, s[8:9]
	v_mul_f32_e32 v8, v5, v2
	v_lshl_add_u32 v2, v7, 2, 0
	v_add_u32_e32 v6, s22, v45
	v_add_u32_e32 v2, 0x20080, v2
	ds_add_rtn_u32 v9, v2, v213
	v_lshl_or_b32 v2, v6, 2, v35
	v_ashrrev_i32_e32 v3, 31, v2
	v_readlane_b32 s0, v253, 30
	v_lshlrev_b64 v[2:3], 2, v[2:3]
	v_readlane_b32 s1, v253, 31
	s_nop 1
	v_lshl_add_u64 v[4:5], s[0:1], 0, v[2:3]
	v_readlane_b32 s0, v253, 32
	v_readlane_b32 s1, v253, 33
	global_store_dword v[4:5], v7, off
	s_nop 0
	v_lshl_add_u64 v[4:5], s[0:1], 0, v[2:3]
	v_readlane_b32 s0, v253, 34
	v_readlane_b32 s1, v253, 35
	global_store_dword v[4:5], v8, off
	s_nop 0
	v_lshl_add_u64 v[2:3], s[0:1], 0, v[2:3]
	s_waitcnt lgkmcnt(0)
	global_store_dword v[2:3], v9, off
; DI float wave_max(float v) { for (int o = 32; o >= 1; o >>= 1) v = fmaxf(v, shx(v, o)); return v; }
; DI void router_phase(const P& p, int l, int ntok, unsigned char* lds) {
;     ...
; #pragma unroll
;     for (int q = 0; q < 4; ++q) {
;       int tl = w * 4 + q;
;       int tok = tbase + c0 + tl;
;       bool valid = (c0 + tl) < per;
;       float v = br[r];
; #pragma unroll
;       for (int k = 0; k < 8; ++k) v += part[(k * 32 + tl) * 33 + r];
;       int se[4]; float sv[4];
; #pragma unroll
;       for (int k = 0; k < 4; ++k) {
;         float m = wave_max(v);
;         unsigned long long mask = __ballot(v == m);
;         int idx = __ffsll((long long)mask) - 1;
;         se[k] = idx & 31; sv[k] = m;
;         if (r == (idx & 31)) v = -3.0e38f;
;       }
;       float e1 = __expf(sv[1] - sv[0]), e2 = __expf(sv[2] - sv[0]), e3 = __expf(sv[3] - sv[0]);
.LBB0_1266:
	s_or_b64 exec, exec, s[16:17]
	global_load_dword v2, v[30:31], off
	ds_read_b32 v3, v74 offset:264
	v_mov_b32_e32 v4, v215
	v_mov_b32_e32 v5, v215
	v_mov_b32_e32 v6, v215
	v_mov_b32_e32 v7, v215
	s_waitcnt vmcnt(0) lgkmcnt(0)
	v_add_f32_e32 v2, v2, v3
	ds_read_b32 v3, v73 offset:4620
	s_waitcnt lgkmcnt(0)
	v_add_f32_e32 v2, v2, v3
	ds_read_b32 v3, v73 offset:8844
	s_waitcnt lgkmcnt(0)
	v_add_f32_e32 v2, v2, v3
	ds_read_b32 v3, v73 offset:13068
	s_waitcnt lgkmcnt(0)
	v_add_f32_e32 v2, v2, v3
	ds_read_b32 v3, v73 offset:17292
	s_waitcnt lgkmcnt(0)
	v_add_f32_e32 v2, v2, v3
	ds_read_b32 v3, v73 offset:21516
	s_waitcnt lgkmcnt(0)
	v_add_f32_e32 v2, v2, v3
	ds_read_b32 v3, v73 offset:25740
	s_waitcnt lgkmcnt(0)
	v_add_f32_e32 v2, v2, v3
	ds_read_b32 v3, v73 offset:29964
	s_waitcnt lgkmcnt(0)
	v_add_f32_e32 v3, v2, v3
	v_mov_b32_e32 v2, v215
	s_nop 0
	v_lshlrev_b32_e32 v2, 2, v2
	v_bitop3_b32 v2, v2, s76, v220 bitop3:0x6c
	s_nop 1
	v_max_f32_dpp v150, v3, v3 quad_perm:[1,0,3,2] row_mask:0xf bank_mask:0xf
	s_nop 1
	v_max_f32_dpp v150, v150, v150 quad_perm:[2,3,0,1] row_mask:0xf bank_mask:0xf
	s_nop 1
	v_max_f32_dpp v150, v150, v150 row_half_mirror row_mask:0xf bank_mask:0xf
	s_nop 1
	v_max_f32_dpp v150, v150, v150 row_mirror row_mask:0xf bank_mask:0xf
	s_nop 1
	v_max_f32_dpp v150, v150, v150 row_bcast:15 row_mask:0xa bank_mask:0xf
	s_nop 1
	v_max_f32_dpp v150, v150, v150 row_bcast:31 row_mask:0xc bank_mask:0xf
	s_nop 1
	v_readlane_b32 s32, v150, 63
	s_nop 1
	v_mov_b32_e32 v2, s32
	v_lshlrev_b32_e32 v4, 2, v4
	v_bitop3_b32 v4, v4, 64, v220 bitop3:0x6c
	s_waitcnt lgkmcnt(0)
	v_max_f32_e32 v2, v2, v2
	v_max_f32_e32 v2, v3, v2
	v_mov_b32_e32 v4, v2
	s_waitcnt lgkmcnt(0)
	v_max_f32_e32 v4, v4, v4
	v_max_f32_e32 v2, v2, v4
	v_mov_b32_e32 v4, v215
	s_nop 0
	v_lshlrev_b32_e32 v4, 2, v4
	v_bitop3_b32 v4, v4, 32, v220 bitop3:0x6c
	v_mov_b32_e32 v4, v2
	s_waitcnt lgkmcnt(0)
	v_max_f32_e32 v4, v4, v4
	v_max_f32_e32 v2, v2, v4
	v_mov_b32_e32 v4, v215
	s_nop 0
	v_lshlrev_b32_e32 v4, 2, v4
	v_bitop3_b32 v4, v4, 16, v220 bitop3:0x6c
	v_mov_b32_e32 v4, v2
	s_waitcnt lgkmcnt(0)
	v_max_f32_e32 v4, v4, v4
	v_max_f32_e32 v2, v2, v4
	v_mov_b32_e32 v4, v215
	s_nop 0
	v_lshlrev_b32_e32 v4, 2, v4
	v_bitop3_b32 v4, v4, 8, v220 bitop3:0x6c
	v_mov_b32_e32 v4, v2
	s_waitcnt lgkmcnt(0)
	v_max_f32_e32 v4, v4, v4
	v_max_f32_e32 v2, v2, v4
	v_mov_b32_e32 v4, v215
	s_nop 0
	v_lshlrev_b32_e32 v4, 2, v4
	v_bitop3_b32 v4, v4, 4, v220 bitop3:0x6c
	v_mov_b32_e32 v4, v2
	s_waitcnt lgkmcnt(0)
	v_max_f32_e32 v4, v4, v4
	v_max_f32_e32 v2, v2, v4
	v_cmp_eq_f32_e32 vcc, v3, v2
	s_ff1_i32_b64 s0, vcc
	s_and_b32 s0, s0, 31
	s_cmp_lg_u64 vcc, 0
	s_cselect_b32 s23, s0, 31
	v_cmp_ne_u32_e32 vcc, s23, v37
	s_nop 1
	v_cndmask_b32_e32 v4, v223, v3, vcc
	v_mov_b32_e32 v3, v215
	s_nop 0
	v_lshlrev_b32_e32 v3, 2, v3
	v_bitop3_b32 v3, v3, s76, v220 bitop3:0x6c
	s_nop 1
	v_max_f32_dpp v150, v4, v4 quad_perm:[1,0,3,2] row_mask:0xf bank_mask:0xf
	s_nop 1
	v_max_f32_dpp v150, v150, v150 quad_perm:[2,3,0,1] row_mask:0xf bank_mask:0xf
	s_nop 1
	v_max_f32_dpp v150, v150, v150 row_half_mirror row_mask:0xf bank_mask:0xf
	s_nop 1
	v_max_f32_dpp v150, v150, v150 row_mirror row_mask:0xf bank_mask:0xf
	s_nop 1
	v_max_f32_dpp v150, v150, v150 row_bcast:15 row_mask:0xa bank_mask:0xf
	s_nop 1
	v_max_f32_dpp v150, v150, v150 row_bcast:31 row_mask:0xc bank_mask:0xf
	s_nop 1
	v_readlane_b32 s32, v150, 63
	s_nop 1
	v_mov_b32_e32 v3, s32
	v_lshlrev_b32_e32 v5, 2, v5
	v_bitop3_b32 v5, v5, 64, v220 bitop3:0x6c
	s_waitcnt lgkmcnt(0)
	v_max_f32_e32 v3, v3, v3
	v_max_f32_e32 v3, v4, v3
	v_mov_b32_e32 v5, v3
	s_waitcnt lgkmcnt(0)
	v_max_f32_e32 v5, v5, v5
	v_max_f32_e32 v3, v3, v5
	v_mov_b32_e32 v5, v215
	s_nop 0
	v_lshlrev_b32_e32 v5, 2, v5
	v_bitop3_b32 v5, v5, 32, v220 bitop3:0x6c
	v_mov_b32_e32 v5, v3
	s_waitcnt lgkmcnt(0)
	v_max_f32_e32 v5, v5, v5
	v_max_f32_e32 v3, v3, v5
	v_mov_b32_e32 v5, v215
	s_nop 0
	v_lshlrev_b32_e32 v5, 2, v5
	v_bitop3_b32 v5, v5, 16, v220 bitop3:0x6c
	v_mov_b32_e32 v5, v3
	s_waitcnt lgkmcnt(0)
	v_max_f32_e32 v5, v5, v5
	v_max_f32_e32 v3, v3, v5
	v_mov_b32_e32 v5, v215
	s_nop 0
	v_lshlrev_b32_e32 v5, 2, v5
	v_bitop3_b32 v5, v5, 8, v220 bitop3:0x6c
	v_mov_b32_e32 v5, v3
	s_waitcnt lgkmcnt(0)
	v_max_f32_e32 v5, v5, v5
	v_max_f32_e32 v3, v3, v5
	v_mov_b32_e32 v5, v215
	s_nop 0
	v_lshlrev_b32_e32 v5, 2, v5
	v_bitop3_b32 v5, v5, 4, v220 bitop3:0x6c
	v_mov_b32_e32 v5, v3
	s_waitcnt lgkmcnt(0)
	v_max_f32_e32 v5, v5, v5
	v_max_f32_e32 v3, v3, v5
	v_cmp_eq_f32_e32 vcc, v4, v3
	s_ff1_i32_b64 s0, vcc
	s_and_b32 s0, s0, 31
	s_cmp_lg_u64 vcc, 0
	s_cselect_b32 s24, s0, 31
	v_cmp_ne_u32_e32 vcc, s24, v37
	s_nop 1
	v_cndmask_b32_e32 v5, v223, v4, vcc
	v_mov_b32_e32 v4, v215
	s_nop 0
	v_lshlrev_b32_e32 v4, 2, v4
	v_bitop3_b32 v4, v4, s76, v220 bitop3:0x6c
	s_nop 1
	v_max_f32_dpp v150, v5, v5 quad_perm:[1,0,3,2] row_mask:0xf bank_mask:0xf
	s_nop 1
	v_max_f32_dpp v150, v150, v150 quad_perm:[2,3,0,1] row_mask:0xf bank_mask:0xf
	s_nop 1
	v_max_f32_dpp v150, v150, v150 row_half_mirror row_mask:0xf bank_mask:0xf
	s_nop 1
	v_max_f32_dpp v150, v150, v150 row_mirror row_mask:0xf bank_mask:0xf
	s_nop 1
	v_max_f32_dpp v150, v150, v150 row_bcast:15 row_mask:0xa bank_mask:0xf
	s_nop 1
	v_max_f32_dpp v150, v150, v150 row_bcast:31 row_mask:0xc bank_mask:0xf
	s_nop 1
	v_readlane_b32 s32, v150, 63
	s_nop 1
	v_mov_b32_e32 v4, s32
	v_lshlrev_b32_e32 v6, 2, v6
	v_bitop3_b32 v6, v6, 64, v220 bitop3:0x6c
	s_waitcnt lgkmcnt(0)
; DI float wave_max(float v) { for (int o = 32; o >= 1; o >>= 1) v = fmaxf(v, shx(v, o)); return v; }
; DI void router_phase(const P& p, int l, int ntok, unsigned char* lds) {
;     ...
;       int se[4]; float sv[4];
; #pragma unroll
;       for (int k = 0; k < 4; ++k) {
;         float m = wave_max(v);
;         unsigned long long mask = __ballot(v == m);
;         int idx = __ffsll((long long)mask) - 1;
;         se[k] = idx & 31; sv[k] = m;
;         if (r == (idx & 31)) v = -3.0e38f;
;       }
;       float e1 = __expf(sv[1] - sv[0]), e2 = __expf(sv[2] - sv[0]), e3 = __expf(sv[3] - sv[0]);
;       float inv = 1.f / (1.f + e1 + e2 + e3);
;       if (valid && lane < 4) {
;         int e = lane == 0 ? se[0] : lane == 1 ? se[1] : lane == 2 ? se[2] : se[3];
;         float gt = (lane == 0 ? 1.f : lane == 1 ? e1 : lane == 2 ? e2 : e3) * inv;
;         int lp = atomicAdd(&lcnt[e], 1);
;         TOKE[tok * 4 + lane] = e; TOKG[tok * 4 + lane] = gt; TOKLP[tok * 4 + lane] = lp;
;       }
;     }
;     __syncthreads();
;   }
	v_max_f32_e32 v4, v4, v4
	v_max_f32_e32 v4, v5, v4
	v_mov_b32_e32 v6, v4
	s_waitcnt lgkmcnt(0)
	v_max_f32_e32 v6, v6, v6
	v_max_f32_e32 v4, v4, v6
	v_mov_b32_e32 v6, v215
	s_nop 0
	v_lshlrev_b32_e32 v6, 2, v6
	v_bitop3_b32 v6, v6, 32, v220 bitop3:0x6c
	v_mov_b32_e32 v6, v4
	s_waitcnt lgkmcnt(0)
	v_max_f32_e32 v6, v6, v6
	v_max_f32_e32 v4, v4, v6
	v_mov_b32_e32 v6, v215
	s_nop 0
	v_lshlrev_b32_e32 v6, 2, v6
	v_bitop3_b32 v6, v6, 16, v220 bitop3:0x6c
	v_mov_b32_e32 v6, v4
	s_waitcnt lgkmcnt(0)
	v_max_f32_e32 v6, v6, v6
	v_max_f32_e32 v4, v4, v6
	v_mov_b32_e32 v6, v215
	s_nop 0
	v_lshlrev_b32_e32 v6, 2, v6
	v_bitop3_b32 v6, v6, 8, v220 bitop3:0x6c
	v_mov_b32_e32 v6, v4
	s_waitcnt lgkmcnt(0)
	v_max_f32_e32 v6, v6, v6
	v_max_f32_e32 v4, v4, v6
	v_mov_b32_e32 v6, v215
	s_nop 0
	v_lshlrev_b32_e32 v6, 2, v6
	v_bitop3_b32 v6, v6, 4, v220 bitop3:0x6c
	v_mov_b32_e32 v6, v4
	s_waitcnt lgkmcnt(0)
	v_max_f32_e32 v6, v6, v6
	v_max_f32_e32 v4, v4, v6
	v_cmp_eq_f32_e32 vcc, v5, v4
	s_ff1_i32_b64 s0, vcc
	s_and_b32 s0, s0, 31
	s_cmp_lg_u64 vcc, 0
	s_cselect_b32 s25, s0, 31
	v_cmp_ne_u32_e32 vcc, s25, v37
	s_nop 1
	v_cndmask_b32_e32 v6, v223, v5, vcc
	v_mov_b32_e32 v5, v215
	v_cmp_gt_i32_e32 vcc, s21, v68
	v_lshlrev_b32_e32 v5, 2, v5
	v_bitop3_b32 v5, v5, s76, v220 bitop3:0x6c
	s_nop 1
	v_max_f32_dpp v150, v6, v6 quad_perm:[1,0,3,2] row_mask:0xf bank_mask:0xf
	s_nop 1
	v_max_f32_dpp v150, v150, v150 quad_perm:[2,3,0,1] row_mask:0xf bank_mask:0xf
	s_nop 1
	v_max_f32_dpp v150, v150, v150 row_half_mirror row_mask:0xf bank_mask:0xf
	s_nop 1
	v_max_f32_dpp v150, v150, v150 row_mirror row_mask:0xf bank_mask:0xf
	s_nop 1
	v_max_f32_dpp v150, v150, v150 row_bcast:15 row_mask:0xa bank_mask:0xf
	s_nop 1
	v_max_f32_dpp v150, v150, v150 row_bcast:31 row_mask:0xc bank_mask:0xf
	s_nop 1
	v_readlane_b32 s32, v150, 63
	s_nop 1
	v_mov_b32_e32 v5, s32
	v_lshlrev_b32_e32 v7, 2, v7
	v_bitop3_b32 v7, v7, 64, v220 bitop3:0x6c
	s_and_b64 s[26:27], vcc, s[6:7]
	s_waitcnt lgkmcnt(0)
	v_max_f32_e32 v5, v5, v5
	v_max_f32_e32 v5, v6, v5
	v_mov_b32_e32 v7, v5
	s_waitcnt lgkmcnt(0)
	v_max_f32_e32 v7, v7, v7
	v_max_f32_e32 v5, v5, v7
	v_mov_b32_e32 v7, v215
	s_nop 0
	v_lshlrev_b32_e32 v7, 2, v7
	v_bitop3_b32 v7, v7, 32, v220 bitop3:0x6c
	v_mov_b32_e32 v7, v5
	s_waitcnt lgkmcnt(0)
	v_max_f32_e32 v7, v7, v7
	v_max_f32_e32 v5, v5, v7
	v_mov_b32_e32 v7, v215
	s_nop 0
	v_lshlrev_b32_e32 v7, 2, v7
	v_bitop3_b32 v7, v7, 16, v220 bitop3:0x6c
	v_mov_b32_e32 v7, v5
	s_waitcnt lgkmcnt(0)
	v_max_f32_e32 v7, v7, v7
	v_max_f32_e32 v5, v5, v7
	v_mov_b32_e32 v7, v215
	s_nop 0
	v_lshlrev_b32_e32 v7, 2, v7
	v_bitop3_b32 v7, v7, 8, v220 bitop3:0x6c
	v_mov_b32_e32 v7, v5
	s_waitcnt lgkmcnt(0)
	v_max_f32_e32 v7, v7, v7
	v_max_f32_e32 v5, v5, v7
	v_mov_b32_e32 v7, v215
	s_nop 0
	v_lshlrev_b32_e32 v7, 2, v7
	v_bitop3_b32 v7, v7, 4, v220 bitop3:0x6c
	v_mov_b32_e32 v7, v5
	s_waitcnt lgkmcnt(0)
	v_max_f32_e32 v7, v7, v7
	v_max_f32_e32 v5, v5, v7
	v_cmp_eq_f32_e64 s[0:1], v6, v5
	s_and_saveexec_b64 s[16:17], s[26:27]
	s_cbranch_execz .LBB0_1239
	v_sub_f32_e32 v5, v5, v2
	v_sub_f32_e32 v4, v4, v2
	v_sub_f32_e32 v2, v3, v2
	v_mul_f32_e32 v2, 0x3fb8aa3b, v2
	v_mul_f32_e32 v4, 0x3fb8aa3b, v4
	v_exp_f32_e32 v2, v2
	v_mul_f32_e32 v5, 0x3fb8aa3b, v5
	v_exp_f32_e32 v3, v4
	v_exp_f32_e32 v4, v5
	v_add_f32_e32 v5, 1.0, v2
	s_ff1_i32_b64 s21, s[0:1]
	v_add_f32_e32 v5, v5, v3
	v_add_f32_e32 v5, v5, v4
	v_div_scale_f32 v6, s[26:27], v5, v5, 1.0
	v_rcp_f32_e32 v7, v6
	s_and_b32 s21, s21, 31
	s_cmp_lg_u64 s[0:1], 0
	s_cselect_b32 s0, s21, 31
	v_fma_f32 v8, -v6, v7, 1.0
	v_fmac_f32_e32 v7, v8, v7
	v_div_scale_f32 v8, vcc, 1.0, v5, 1.0
	v_mul_f32_e32 v9, v8, v7
	v_fma_f32 v10, -v6, v9, v8
	v_fmac_f32_e32 v9, v10, v7
	v_fma_f32 v6, -v6, v9, v8
	v_div_fmas_f32 v6, v6, v7, v9
	v_mov_b32_e32 v7, s0
	v_mov_b32_e32 v8, s25
	v_cndmask_b32_e64 v7, v7, v8, s[12:13]
	v_mov_b32_e32 v8, s24
	v_cndmask_b32_e64 v3, v4, v3, s[12:13]
	v_cndmask_b32_e64 v7, v7, v8, s[10:11]
	v_mov_b32_e32 v8, s23
	v_cndmask_b32_e64 v2, v3, v2, s[10:11]
	v_div_fixup_f32 v5, v6, v5, 1.0
	v_cndmask_b32_e64 v7, v7, v8, s[8:9]
	v_cndmask_b32_e64 v2, v2, 1.0, s[8:9]
	v_mul_f32_e32 v8, v5, v2
	v_lshl_add_u32 v2, v7, 2, 0
	v_add_u32_e32 v6, s22, v68
	v_add_u32_e32 v2, 0x20080, v2
	ds_add_rtn_u32 v9, v2, v213
	v_lshl_or_b32 v2, v6, 2, v35
	v_ashrrev_i32_e32 v3, 31, v2
	v_readlane_b32 s0, v253, 30
	v_lshlrev_b64 v[2:3], 2, v[2:3]
	v_readlane_b32 s1, v253, 31
	s_nop 1
	v_lshl_add_u64 v[4:5], s[0:1], 0, v[2:3]
	v_readlane_b32 s0, v253, 32
	v_readlane_b32 s1, v253, 33
	global_store_dword v[4:5], v7, off
	s_nop 0
	v_lshl_add_u64 v[4:5], s[0:1], 0, v[2:3]
	v_readlane_b32 s0, v253, 34
	v_readlane_b32 s1, v253, 35
	global_store_dword v[4:5], v8, off
	s_nop 0
	v_lshl_add_u64 v[2:3], s[0:1], 0, v[2:3]
	s_waitcnt lgkmcnt(0)
	global_store_dword v[2:3], v9, off
	s_branch .LBB0_1239
